# scan items re-mapped so each SIMD's two waves get 5 full chunks (3+2) instead of 3+3 or 2+2; on top of MFMA finalize
# speedup vs baseline: 1.0091x; 1.0091x over previous
; #define LAS __attribute__((address_space(3)))
; DI void chunk_decode(int g, int& seq, int& c) { if (g < NCP) { seq = 0; c = g; } else { seq = 1 + (g - NCP) / NCS; c = (g - NCP) % NCS; } }
; DI void chunk_range(int c, int& t0, int& t1) { if (c == 0) { t0 = 0; t1 = 16; } else { t0 = 16 + 128 * (c - 1); t1 = t0 + 128; } }
; template <int DIR> DI void scan_item(const Params& p, int l, LAS float* L, LAS float* CL, int item, int lane) {
;     ...
;     const int g = item >> 3, hd = (item >> 1) & 3;
;     int seq, c; chunk_decode(g, seq, c); int t0, t1; chunk_range(c, t0, t1);
;     const int base = seq_start(seq), nsub = (t1 - t0) >> 3, ch = hd * 64 + lane;
;     const int la = lane >> 2, lb = lane & 3;
;     CL[lane] = p.in[16][(size_t)l * 256 + ch]; CL[64 + lane] = p.in[17][(size_t)l * 256 + ch];
;     f32x2 SU[4][8], SP[4][8];
; #pragma unroll
;     for (int ri = 0; ri < 4; ++ri)
; #pragma unroll
;         for (int cp = 0; cp < 8; ++cp) { SU[ri][cp] = (f32x2){0.f, 0.f}; SP[ri][cp] = (f32x2){(4 * la + ri == 16 * lb + 2 * cp) ? 1.f : 0.f, (4 * la + ri == 16 * lb + 2 * cp + 1) ? 1.f : 0.f}; }
;     const int ss = lane >> 3, cg = lane & 7;
; DI void phase_scan(int wv, const Params& p, int l, LAS unsigned char* lds) {
;     const int tid = tid_(wv), lane = tid & 63, w = tid >> 6, gw = blockIdx.x * 8 + w, nw = gridDim.x * 8;
;     LAS float* L = (LAS float*)(lds + w * 12288); LAS float* CL = (LAS float*)(lds + 98304 + w * 512);
;     for (int item = gw; item < NCH * 8; item += nw) {
;         if (item & 1) scan_item<1>(p, l, L, CL, item, lane); else scan_item<0>(p, l, L, CL, item, lane);
.LBB0_905:
	s_or_b64 exec, exec, s[16:17]
	v_mov_b32_e32 v0, v254
	v_readlane_b32 s6, v255, 2
	v_add_u32_e32 v1, s33, v0
	v_ashrrev_i32_e32 v2, 6, v1
	s_lshr_b32 vcc_lo, s33, 6
	s_lshr_b32 s98, s2, 1
	s_mul_i32 s99, s98, 5
	s_and_b32 s100, s2, 1
	s_lshr_b32 s101, vcc_lo, 2
	s_cmp_eq_u32 s100, s101
	s_cbranch_scc0 .Lsb_two_1
	s_lshl_b32 s101, s101, 1
	s_add_u32 s98, s99, s101
	s_add_u32 s99, s98, 1
	s_add_u32 s100, s98, 2
	s_sub_i32 s101, s100, 0x70
	s_max_i32 s101, s101, 0
	s_lshr_b32 s101, s101, 4
	s_add_u32 s100, s100, s101
	s_add_u32 s100, s100, 1
	s_lshl_b32 s100, s100, 3
	s_or_b32 s100, s100, vcc_lo
	s_branch .Lsb_common_1
.Lsb_two_1:
	s_xor_b32 s101, s101, 1
	s_mul_i32 s101, s101, 3
	s_add_u32 s101, s99, s101
	s_mul_i32 s100, s98, 17
	s_add_u32 s100, s100, 0x70
	s_cmp_eq_u32 s98, 0
	s_cselect_b32 s100, 0, s100
	s_lshl_b32 s100, s100, 3
	s_or_b32 s100, s100, vcc_lo
	s_cmp_gt_u32 s98, 32
	s_cselect_b32 s100, 0x7fff, s100
	s_mov_b32 s98, s101
	s_add_u32 s99, s98, 1
.Lsb_common_1:
	s_sub_i32 s101, s98, 0x70
	s_max_i32 s101, s101, 0
	s_lshr_b32 s101, s101, 4
	s_add_u32 s98, s98, s101
	s_add_u32 s98, s98, 1
	s_lshl_b32 s98, s98, 3
	s_or_b32 s98, s98, vcc_lo
	s_sub_i32 s101, s99, 0x70
	s_max_i32 s101, s101, 0
	s_lshr_b32 s101, s101, 4
	s_add_u32 s99, s99, s101
	s_add_u32 s99, s99, 1
	s_lshl_b32 s99, s99, 3
	s_or_b32 s99, s99, vcc_lo
	v_mov_b32_e32 v64, s98
	s_movk_i32 s6, 0x1508
	v_cmp_gt_i32_e32 vcc, s6, v64
	s_and_saveexec_b64 s[62:63], vcc
	s_cbranch_execz .LBB0_928
	s_load_dwordx4 s[28:31], s[0:1], 0x120
	s_load_dwordx4 s[36:39], s[0:1], 0x80
	s_movk_i32 s6, 0x3000
	v_mul_lo_u32 v3, v2, s6
	s_add_i32 s6, 0, 0x18000
	s_waitcnt lgkmcnt(0)
	s_add_u32 s64, s30, 0x32908000
	s_addc_u32 s65, s31, 0
	s_add_u32 s66, s30, 0x35168000
	s_addc_u32 s67, s31, 0
	s_add_u32 s68, s30, 0x379c8000
	s_addc_u32 s69, s31, 0
	v_and_b32_e32 v6, 3, v0
	s_add_u32 s70, s28, 0x109d0000
	v_and_b32_e32 v5, 60, v0
	v_lshlrev_b32_e32 v7, 4, v6
	s_addc_u32 s71, s29, 0
	v_cmp_eq_u32_e32 vcc, v5, v7
	v_or_b32_e32 v8, 4, v7
	s_add_u32 s72, s28, 0xdfc0000
	v_cndmask_b32_e64 v66, 0, 1.0, vcc
	v_cmp_eq_u32_e32 vcc, v5, v8
	v_or_b32_e32 v8, 8, v7
	s_addc_u32 s73, s29, 0
	v_and_b32_e32 v93, 63, v0
	v_cndmask_b32_e64 v70, 0, 1.0, vcc
	v_cmp_eq_u32_e32 vcc, v5, v8
	v_or_b32_e32 v8, 12, v7
	s_add_u32 s74, s28, 0xb5b0000
	v_cndmask_b32_e64 v72, 0, 1.0, vcc
	v_cmp_eq_u32_e32 vcc, v5, v8
	v_or_b32_e32 v8, 3, v93
	v_or_b32_e32 v9, 3, v7
	s_addc_u32 s75, s29, 0
	v_cndmask_b32_e64 v74, 0, 1.0, vcc
	v_cmp_eq_u32_e32 vcc, v8, v9
	v_or_b32_e32 v9, 7, v7
	s_add_u32 s76, s30, 0x1bda8000
	v_cndmask_b32_e64 v85, 0, 1.0, vcc
	v_cmp_eq_u32_e32 vcc, v8, v9
	v_or_b32_e32 v9, 11, v7
	s_addc_u32 s77, s31, 0
	v_cndmask_b32_e64 v87, 0, 1.0, vcc
	v_cmp_eq_u32_e32 vcc, v8, v9
	v_or_b32_e32 v9, 15, v7
	s_add_u32 s78, s30, 0x20e68000
	v_cndmask_b32_e64 v89, 0, 1.0, vcc
	v_cmp_eq_u32_e32 vcc, v8, v9
	v_bfe_u32 v181, v0, 3, 3
	v_lshlrev_b32_e32 v8, 3, v0
	s_addc_u32 s79, s31, 0
	v_lshlrev_b32_e32 v0, 2, v0
	s_movk_i32 s8, 0xf0
	s_add_u32 s80, s30, 0x19548000
	v_and_or_b32 v0, v0, s8, v3
	v_and_b32_e32 v183, 56, v8
	s_addc_u32 s81, s31, 0
	v_add_u32_e32 v0, 0, v0
	v_add_u32_e32 v4, 0, v3
	v_lshl_add_u32 v2, v2, 9, s6
	v_mov_b32_e32 v69, 0
	v_mul_u32_u24_e32 v8, 0x600, v181
	v_lshlrev_b32_e32 v9, 2, v183
	v_and_b32_e32 v1, 64, v1
	s_add_u32 s82, s30, 0x1e608000
	v_add_u32_e32 v186, 0x500, v0
	v_lshl_or_b32 v0, v6, 6, v3
	s_movk_i32 s86, 0xfc00
	v_lshl_add_u32 v179, v93, 2, v2
	v_mov_b32_e32 v67, v69
	v_mov_b32_e32 v71, v69
	v_mov_b32_e32 v73, v69
	v_mov_b32_e32 v75, v69
	v_mov_b32_e32 v76, v69
	v_mov_b32_e32 v77, v66
	v_mov_b32_e32 v78, v69
	v_mov_b32_e32 v79, v70
	v_mov_b32_e32 v80, v69
	v_mov_b32_e32 v81, v72
	v_mov_b32_e32 v82, v69
	v_mov_b32_e32 v83, v74
	v_mov_b32_e32 v84, v69
	v_mov_b32_e32 v86, v69
	v_mov_b32_e32 v88, v69
	v_cndmask_b32_e64 v91, 0, 1.0, vcc
	v_mov_b32_e32 v90, v69
	v_add3_u32 v184, v4, v8, v9
	v_add_u32_e32 v185, v2, v9
	v_cmp_eq_u32_e64 s[6:7], 0, v6
	v_cmp_eq_u32_e64 s[12:13], 1, v6
	v_cmp_eq_u32_e64 s[14:15], 2, v6
	v_cmp_eq_u32_e64 s[16:17], 3, v6
	v_lshl_or_b32 v92, v5, 6, v7
	v_cmp_ne_u32_e64 s[18:19], 0, v1
	s_addc_u32 s83, s31, 0
	v_add_u32_e32 v187, 0, v0
	s_mov_b64 s[84:85], 0
	v_lshlrev_b32_e32 v188, 1, v93
	s_movk_i32 s8, 0x810
	s_mov_b32 s87, -1
	v_mov_b32_e32 v189, 0x3800
	s_branch .LBB0_909

; DI unsigned pack2(float lo, float hi) { f32x2 v = {lo, hi}; bf16v2 r = __builtin_convertvector(v, bf16v2); return __builtin_bit_cast(unsigned, r); }
; template <int DIR> DI void scan_item(const Params& p, int l, LAS float* L, LAS float* CL, int item, int lane) {
;     ...
; #pragma unroll
;     for (int ri = 0; ri < 4; ++ri) {
;         const size_t o = ((size_t)item * 64 + 4 * la + ri) * 64 + 16 * lb;
; #pragma unroll
;         for (int hh = 0; hh < 2; ++hh) {
;             u32x4 x = {pack2(SU[ri][4 * hh][0], SU[ri][4 * hh][1]), pack2(SU[ri][4 * hh + 1][0], SU[ri][4 * hh + 1][1]), pack2(SU[ri][4 * hh + 2][0], SU[ri][4 * hh + 2][1]), pack2(SU[ri][4 * hh + 3][0], SU[ri][4 * hh + 3][1])};
;             u32x4 y = {pack2(SP[ri][4 * hh][0], SP[ri][4 * hh][1]), pack2(SP[ri][4 * hh + 1][0], SP[ri][4 * hh + 1][1]), pack2(SP[ri][4 * hh + 2][0], SP[ri][4 * hh + 2][1]), pack2(SP[ri][4 * hh + 3][0], SP[ri][4 * hh + 3][1])};
;             *(u32x4*)(UU + o + 8 * hh) = x; *(u32x4*)(PT + o + 8 * hh) = y;
;         }
;     }
; DI void phase_scan(int wv, const Params& p, int l, LAS unsigned char* lds) {
;     ...
;     for (int item = gw; item < NCH * 8; item += nw) {
.LBB0_908:
	s_or_b64 exec, exec, s[88:89]
	v_ashrrev_i32_e32 v65, 31, v64
	v_lshlrev_b64 v[126:127], 13, v[64:65]
	v_lshl_or_b32 v126, v92, 1, v126
	v_lshl_add_u64 v[128:129], s[74:75], 0, v[126:127]
	v_lshl_add_u64 v[130:131], s[72:73], 0, v[126:127]
	v_cvt_pk_bf16_f32 v60, v124, v125
	v_cvt_pk_bf16_f32 v62, v122, v123
	global_store_dwordx4 v[128:129], v[56:59], off
	global_store_dwordx4 v[130:131], v[60:63], off
	v_cvt_pk_bf16_f32 v52, v120, v121
	v_cvt_pk_bf16_f32 v54, v118, v119
	global_store_dwordx4 v[128:129], v[48:51], off offset:16
	global_store_dwordx4 v[130:131], v[52:55], off offset:16
	v_cvt_pk_bf16_f32 v44, v116, v117
	v_or_b32_e32 v48, 0x80, v126
	v_mov_b32_e32 v49, v127
	v_lshl_add_u64 v[50:51], s[74:75], 0, v[48:49]
	v_lshl_add_u64 v[48:49], s[72:73], 0, v[48:49]
	v_cvt_pk_bf16_f32 v46, v114, v115
	global_store_dwordx4 v[50:51], v[40:43], off
	global_store_dwordx4 v[48:49], v[44:47], off
	v_cvt_pk_bf16_f32 v36, v112, v113
	v_cvt_pk_bf16_f32 v38, v110, v111
	global_store_dwordx4 v[50:51], v[32:35], off offset:16
	global_store_dwordx4 v[48:49], v[36:39], off offset:16
	v_mov_b32_e32 v64, s99
	s_mov_b32 s99, s100
	s_movk_i32 s100, 0x7fff
	v_or_b32_e32 v32, 0x100, v126
	v_mov_b32_e32 v33, v127
	s_movk_i32 s9, 0x1507
	v_lshl_add_u64 v[34:35], s[74:75], 0, v[32:33]
	v_or_b32_e32 v126, 0x180, v126
	v_cmp_lt_i32_e32 vcc, s9, v64
	v_lshl_add_u64 v[32:33], s[72:73], 0, v[32:33]
	v_cvt_pk_bf16_f32 v29, v108, v109
	v_cvt_pk_bf16_f32 v31, v106, v107
	global_store_dwordx4 v[34:35], v[24:27], off
	global_store_dwordx4 v[32:33], v[28:31], off
	v_cvt_pk_bf16_f32 v21, v104, v105
	v_cvt_pk_bf16_f32 v23, v102, v103
	global_store_dwordx4 v[34:35], v[16:19], off offset:16
	global_store_dwordx4 v[32:33], v[20:23], off offset:16
	v_cvt_pk_bf16_f32 v1, v96, v97
	v_lshl_add_u64 v[16:17], s[74:75], 0, v[126:127]
	v_lshl_add_u64 v[18:19], s[72:73], 0, v[126:127]
	v_cvt_pk_bf16_f32 v3, v94, v95
	s_or_b64 s[84:85], vcc, s[84:85]
	v_cvt_pk_bf16_f32 v13, v100, v101
	v_cvt_pk_bf16_f32 v15, v98, v99
	global_store_dwordx4 v[16:17], v[8:11], off
	global_store_dwordx4 v[18:19], v[12:15], off
	global_store_dwordx4 v[16:17], v[4:7], off offset:16
	global_store_dwordx4 v[18:19], v[0:3], off offset:16
	s_andn2_b64 exec, exec, s[84:85]
	s_cbranch_execz .LBB0_928

; #define LAS __attribute__((address_space(3)))
; DI void phase_scan(int wv, const Params& p, int l, LAS unsigned char* lds) {
;     const int tid = tid_(wv), lane = tid & 63, w = tid >> 6, gw = blockIdx.x * 8 + w, nw = gridDim.x * 8;
;     LAS float* L = (LAS float*)(lds + w * 12288); LAS float* CL = (LAS float*)(lds + 98304 + w * 512);
;     for (int item = gw; item < NCH * 8; item += nw) {
.LBB0_2539:
	s_or_b64 exec, exec, s[14:15]
	v_mov_b32_e32 v0, v254
	v_readlane_b32 s4, v255, 2
	v_add_u32_e32 v1, s33, v0
	v_ashrrev_i32_e32 v2, 6, v1
	s_lshr_b32 vcc_lo, s33, 6
	s_lshr_b32 s98, s2, 1
	s_mul_i32 s99, s98, 5
	s_and_b32 s100, s2, 1
	s_lshr_b32 s101, vcc_lo, 2
	s_cmp_eq_u32 s100, s101
	s_cbranch_scc0 .Lsb_two_2
	s_lshl_b32 s101, s101, 1
	s_add_u32 s98, s99, s101
	s_add_u32 s99, s98, 1
	s_add_u32 s100, s98, 2
	s_sub_i32 s101, s100, 0x70
	s_max_i32 s101, s101, 0
	s_lshr_b32 s101, s101, 4
	s_add_u32 s100, s100, s101
	s_add_u32 s100, s100, 1
	s_lshl_b32 s100, s100, 3
	s_or_b32 s100, s100, vcc_lo
	s_branch .Lsb_common_2

; #define LAS __attribute__((address_space(3)))
; DI void chunk_decode(int g, int& seq, int& c) { if (g < NCP) { seq = 0; c = g; } else { seq = 1 + (g - NCP) / NCS; c = (g - NCP) % NCS; } }
; DI void chunk_range(int c, int& t0, int& t1) { if (c == 0) { t0 = 0; t1 = 16; } else { t0 = 16 + 128 * (c - 1); t1 = t0 + 128; } }
; template <int DIR> DI void scan_item(const Params& p, int l, LAS float* L, LAS float* CL, int item, int lane) {
;     ...
;     const int g = item >> 3, hd = (item >> 1) & 3;
;     int seq, c; chunk_decode(g, seq, c); int t0, t1; chunk_range(c, t0, t1);
;     const int base = seq_start(seq), nsub = (t1 - t0) >> 3, ch = hd * 64 + lane;
;     const int la = lane >> 2, lb = lane & 3;
;     CL[lane] = p.in[16][(size_t)l * 256 + ch]; CL[64 + lane] = p.in[17][(size_t)l * 256 + ch];
;     f32x2 SU[4][8], SP[4][8];
; #pragma unroll
;     for (int ri = 0; ri < 4; ++ri)
; #pragma unroll
;         for (int cp = 0; cp < 8; ++cp) { SU[ri][cp] = (f32x2){0.f, 0.f}; SP[ri][cp] = (f32x2){(4 * la + ri == 16 * lb + 2 * cp) ? 1.f : 0.f, (4 * la + ri == 16 * lb + 2 * cp + 1) ? 1.f : 0.f}; }
;     const int ss = lane >> 3, cg = lane & 7;
; DI void phase_scan(int wv, const Params& p, int l, LAS unsigned char* lds) {
;     const int tid = tid_(wv), lane = tid & 63, w = tid >> 6, gw = blockIdx.x * 8 + w, nw = gridDim.x * 8;
;     LAS float* L = (LAS float*)(lds + w * 12288); LAS float* CL = (LAS float*)(lds + 98304 + w * 512);
;     for (int item = gw; item < NCH * 8; item += nw) {
.Lsb_common_2:
	s_sub_i32 s101, s98, 0x70
	s_max_i32 s101, s101, 0
	s_lshr_b32 s101, s101, 4
	s_add_u32 s98, s98, s101
	s_add_u32 s98, s98, 1
	s_lshl_b32 s98, s98, 3
	s_or_b32 s98, s98, vcc_lo
	s_sub_i32 s101, s99, 0x70
	s_max_i32 s101, s101, 0
	s_lshr_b32 s101, s101, 4
	s_add_u32 s99, s99, s101
	s_add_u32 s99, s99, 1
	s_lshl_b32 s99, s99, 3
	s_or_b32 s99, s99, vcc_lo
	v_mov_b32_e32 v64, s98
	s_movk_i32 s4, 0x1508
	v_cmp_gt_i32_e32 vcc, s4, v64
	s_and_saveexec_b64 s[46:47], vcc
	s_cbranch_execz .LBB0_2562
	s_load_dwordx4 s[24:27], s[0:1], 0x120
	s_load_dwordx4 s[28:31], s[0:1], 0x80
	s_movk_i32 s4, 0x3000
	v_mul_lo_u32 v3, v2, s4
	s_add_i32 s4, 0, 0x18000
	s_waitcnt lgkmcnt(0)
	s_add_u32 s48, s26, 0x32908000
	s_addc_u32 s49, s27, 0
	s_add_u32 s50, s26, 0x35168000
	s_addc_u32 s51, s27, 0
	s_add_u32 s52, s26, 0x379c8000
	s_addc_u32 s53, s27, 0
	v_and_b32_e32 v6, 3, v0
	s_add_u32 s54, s24, 0x109d0000
	v_and_b32_e32 v5, 60, v0
	v_lshlrev_b32_e32 v7, 4, v6
	s_addc_u32 s55, s25, 0
	v_cmp_eq_u32_e32 vcc, v5, v7
	v_or_b32_e32 v8, 4, v7
	s_add_u32 s56, s24, 0xdfc0000
	v_cndmask_b32_e64 v66, 0, 1.0, vcc
	v_cmp_eq_u32_e32 vcc, v5, v8
	v_or_b32_e32 v8, 8, v7
	s_addc_u32 s57, s25, 0
	v_and_b32_e32 v93, 63, v0
	v_cndmask_b32_e64 v70, 0, 1.0, vcc
	v_cmp_eq_u32_e32 vcc, v5, v8
	v_or_b32_e32 v8, 12, v7
	s_add_u32 s58, s24, 0xb5b0000
	v_cndmask_b32_e64 v72, 0, 1.0, vcc
	v_cmp_eq_u32_e32 vcc, v5, v8
	v_or_b32_e32 v8, 3, v93
	v_or_b32_e32 v9, 3, v7
	s_addc_u32 s59, s25, 0
	v_cndmask_b32_e64 v74, 0, 1.0, vcc
	v_cmp_eq_u32_e32 vcc, v8, v9
	v_or_b32_e32 v9, 7, v7
	s_add_u32 s60, s26, 0x1bda8000
	v_cndmask_b32_e64 v85, 0, 1.0, vcc
	v_cmp_eq_u32_e32 vcc, v8, v9
	v_or_b32_e32 v9, 11, v7
	s_addc_u32 s61, s27, 0
	v_cndmask_b32_e64 v87, 0, 1.0, vcc
	v_cmp_eq_u32_e32 vcc, v8, v9
	v_or_b32_e32 v9, 15, v7
	s_add_u32 s62, s26, 0x20e68000
	v_cndmask_b32_e64 v89, 0, 1.0, vcc
	v_cmp_eq_u32_e32 vcc, v8, v9
	v_bfe_u32 v181, v0, 3, 3
	v_lshlrev_b32_e32 v8, 3, v0
	s_addc_u32 s63, s27, 0
	v_lshlrev_b32_e32 v0, 2, v0
	s_movk_i32 s18, 0xf0
	s_add_u32 s64, s26, 0x19548000
	v_and_or_b32 v0, v0, s18, v3
	v_and_b32_e32 v183, 56, v8
	s_addc_u32 s65, s27, 0
	v_add_u32_e32 v0, 0, v0
	v_add_u32_e32 v4, 0, v3
	v_lshl_add_u32 v2, v2, 9, s4
	v_mov_b32_e32 v69, 0
	v_mul_u32_u24_e32 v8, 0x600, v181
	v_lshlrev_b32_e32 v9, 2, v183
	v_and_b32_e32 v1, 64, v1
	s_add_u32 s66, s26, 0x1e608000
	v_add_u32_e32 v186, 0x500, v0
	v_lshl_or_b32 v0, v6, 6, v3
	s_movk_i32 s70, 0xfc00
	v_lshl_add_u32 v179, v93, 2, v2
	v_mov_b32_e32 v67, v69
	v_mov_b32_e32 v71, v69
	v_mov_b32_e32 v73, v69
	v_mov_b32_e32 v75, v69
	v_mov_b32_e32 v76, v69
	v_mov_b32_e32 v77, v66
	v_mov_b32_e32 v78, v69
	v_mov_b32_e32 v79, v70
	v_mov_b32_e32 v80, v69
	v_mov_b32_e32 v81, v72
	v_mov_b32_e32 v82, v69
	v_mov_b32_e32 v83, v74
	v_mov_b32_e32 v84, v69
	v_mov_b32_e32 v86, v69
	v_mov_b32_e32 v88, v69
	v_cndmask_b32_e64 v91, 0, 1.0, vcc
	v_mov_b32_e32 v90, v69
	v_add3_u32 v184, v4, v8, v9
	v_add_u32_e32 v185, v2, v9
	v_cmp_eq_u32_e64 s[4:5], 0, v6
	v_cmp_eq_u32_e64 s[8:9], 1, v6
	v_cmp_eq_u32_e64 s[10:11], 2, v6
	v_cmp_eq_u32_e64 s[14:15], 3, v6
	v_lshl_or_b32 v92, v5, 6, v7
	v_cmp_ne_u32_e64 s[16:17], 0, v1
	s_addc_u32 s67, s27, 0
	v_add_u32_e32 v187, 0, v0
	s_mov_b64 s[68:69], 0
	v_lshlrev_b32_e32 v188, 1, v93
	s_movk_i32 s41, 0x80
	s_movk_i32 s78, 0x810
	s_mov_b32 s79, 0x8d50000
	s_mov_b32 s80, 0x3ca88000
	s_mov_b32 s71, -1
	s_mov_b32 s81, 0x64f0000
	s_mov_b32 s82, 0x3a228000
	s_movk_i32 s83, 0x1507
	v_mov_b32_e32 v189, 0x3800
	s_branch .LBB0_2543

; DI unsigned pack2(float lo, float hi) { f32x2 v = {lo, hi}; bf16v2 r = __builtin_convertvector(v, bf16v2); return __builtin_bit_cast(unsigned, r); }
; template <int DIR> DI void scan_item(const Params& p, int l, LAS float* L, LAS float* CL, int item, int lane) {
;     ...
; #pragma unroll
;     for (int ri = 0; ri < 4; ++ri) {
;         const size_t o = ((size_t)item * 64 + 4 * la + ri) * 64 + 16 * lb;
; #pragma unroll
;         for (int hh = 0; hh < 2; ++hh) {
;             u32x4 x = {pack2(SU[ri][4 * hh][0], SU[ri][4 * hh][1]), pack2(SU[ri][4 * hh + 1][0], SU[ri][4 * hh + 1][1]), pack2(SU[ri][4 * hh + 2][0], SU[ri][4 * hh + 2][1]), pack2(SU[ri][4 * hh + 3][0], SU[ri][4 * hh + 3][1])};
;             u32x4 y = {pack2(SP[ri][4 * hh][0], SP[ri][4 * hh][1]), pack2(SP[ri][4 * hh + 1][0], SP[ri][4 * hh + 1][1]), pack2(SP[ri][4 * hh + 2][0], SP[ri][4 * hh + 2][1]), pack2(SP[ri][4 * hh + 3][0], SP[ri][4 * hh + 3][1])};
;             *(u32x4*)(UU + o + 8 * hh) = x; *(u32x4*)(PT + o + 8 * hh) = y;
;         }
;     }
; DI void phase_scan(int wv, const Params& p, int l, LAS unsigned char* lds) {
;     ...
;     for (int item = gw; item < NCH * 8; item += nw) {
.LBB0_2542:
	s_or_b64 exec, exec, s[72:73]
	v_ashrrev_i32_e32 v65, 31, v64
	v_lshlrev_b64 v[126:127], 13, v[64:65]
	v_lshl_or_b32 v126, v92, 1, v126
	v_lshl_add_u64 v[128:129], s[58:59], 0, v[126:127]
	v_lshl_add_u64 v[130:131], s[56:57], 0, v[126:127]
	v_cvt_pk_bf16_f32 v60, v124, v125
	v_cvt_pk_bf16_f32 v62, v122, v123
	global_store_dwordx4 v[128:129], v[56:59], off
	global_store_dwordx4 v[130:131], v[60:63], off
	v_cvt_pk_bf16_f32 v52, v120, v121
	v_cvt_pk_bf16_f32 v54, v118, v119
	global_store_dwordx4 v[128:129], v[48:51], off offset:16
	global_store_dwordx4 v[130:131], v[52:55], off offset:16
	v_cvt_pk_bf16_f32 v44, v116, v117
	v_or_b32_e32 v48, 0x80, v126
	v_mov_b32_e32 v49, v127
	v_lshl_add_u64 v[50:51], s[58:59], 0, v[48:49]
	v_lshl_add_u64 v[48:49], s[56:57], 0, v[48:49]
	v_cvt_pk_bf16_f32 v46, v114, v115
	global_store_dwordx4 v[50:51], v[40:43], off
	global_store_dwordx4 v[48:49], v[44:47], off
	v_cvt_pk_bf16_f32 v36, v112, v113
	v_cvt_pk_bf16_f32 v38, v110, v111
	global_store_dwordx4 v[50:51], v[32:35], off offset:16
	global_store_dwordx4 v[48:49], v[36:39], off offset:16
	v_mov_b32_e32 v64, s99
	s_mov_b32 s99, s100
	s_movk_i32 s100, 0x7fff
	v_or_b32_e32 v32, 0x100, v126
	v_mov_b32_e32 v33, v127
	v_lshl_add_u64 v[34:35], s[58:59], 0, v[32:33]
	v_or_b32_e32 v126, 0x180, v126
	v_cmp_lt_i32_e32 vcc, s83, v64
	v_lshl_add_u64 v[32:33], s[56:57], 0, v[32:33]
	v_cvt_pk_bf16_f32 v29, v108, v109
	v_cvt_pk_bf16_f32 v31, v106, v107
	global_store_dwordx4 v[34:35], v[24:27], off
	global_store_dwordx4 v[32:33], v[28:31], off
	v_cvt_pk_bf16_f32 v21, v104, v105
	v_cvt_pk_bf16_f32 v23, v102, v103
	global_store_dwordx4 v[34:35], v[16:19], off offset:16
	global_store_dwordx4 v[32:33], v[20:23], off offset:16
	v_cvt_pk_bf16_f32 v1, v96, v97
	v_lshl_add_u64 v[16:17], s[58:59], 0, v[126:127]
	v_lshl_add_u64 v[18:19], s[56:57], 0, v[126:127]
	v_cvt_pk_bf16_f32 v3, v94, v95
	s_or_b64 s[68:69], vcc, s[68:69]
	v_cvt_pk_bf16_f32 v13, v100, v101
	v_cvt_pk_bf16_f32 v15, v98, v99
	global_store_dwordx4 v[16:17], v[8:11], off
	global_store_dwordx4 v[18:19], v[12:15], off
	global_store_dwordx4 v[16:17], v[4:7], off offset:16
	global_store_dwordx4 v[18:19], v[0:3], off offset:16
	s_andn2_b64 exec, exec, s[68:69]
	s_cbranch_execz .LBB0_2562

; __global__ void __launch_bounds__(512, 2) hybrid_fwd(Params p) {
;     extern __shared__ __attribute__((aligned(16))) unsigned char shm[];
	.amdhsa_kernel _Z10hybrid_fwd6Params
		.amdhsa_group_segment_fixed_size 0
		.amdhsa_private_segment_fixed_size 0
		.amdhsa_kernarg_size 560
		.amdhsa_user_sgpr_count 2
		.amdhsa_user_sgpr_dispatch_ptr 0
		.amdhsa_user_sgpr_queue_ptr 0
		.amdhsa_user_sgpr_kernarg_segment_ptr 1
		.amdhsa_user_sgpr_dispatch_id 0
		.amdhsa_user_sgpr_kernarg_preload_length 0
		.amdhsa_user_sgpr_kernarg_preload_offset 0
		.amdhsa_user_sgpr_private_segment_size 0
		.amdhsa_uses_dynamic_stack 0
		.amdhsa_enable_private_segment 0
		.amdhsa_system_sgpr_workgroup_id_x 1
		.amdhsa_system_sgpr_workgroup_id_y 0
		.amdhsa_system_sgpr_workgroup_id_z 0
		.amdhsa_system_sgpr_workgroup_info 0
		.amdhsa_system_vgpr_workitem_id 2
		.amdhsa_next_free_vgpr 256
		.amdhsa_next_free_sgpr 102
		.amdhsa_accum_offset 256
		.amdhsa_reserve_vcc 1
		.amdhsa_float_round_mode_32 0
		.amdhsa_float_round_mode_16_64 0
		.amdhsa_float_denorm_mode_32 3
		.amdhsa_float_denorm_mode_16_64 3
		.amdhsa_dx10_clamp 1
		.amdhsa_ieee_mode 1
		.amdhsa_fp16_overflow 0
		.amdhsa_tg_split 0
		.amdhsa_exception_fp_ieee_invalid_op 0
		.amdhsa_exception_fp_denorm_src 0
		.amdhsa_exception_fp_ieee_div_zero 0
		.amdhsa_exception_fp_ieee_overflow 0
		.amdhsa_exception_fp_ieee_underflow 0
		.amdhsa_exception_fp_ieee_inexact 0
		.amdhsa_exception_int_div_zero 0
	.end_amdhsa_kernel

; __global__ void __launch_bounds__(512, 2) hybrid_fwd(Params p) {
;     extern __shared__ __attribute__((aligned(16))) unsigned char shm[];
amdhsa.kernels:
  - .agpr_count:     0
    .args:
      - .offset:         0
        .size:           304
        .value_kind:     by_value
      - .offset:         304
        .size:           4
        .value_kind:     hidden_block_count_x
      - .offset:         308
        .size:           4
        .value_kind:     hidden_block_count_y
      - .offset:         312
        .size:           4
        .value_kind:     hidden_block_count_z
      - .offset:         316
        .size:           2
        .value_kind:     hidden_group_size_x
      - .offset:         318
        .size:           2
        .value_kind:     hidden_group_size_y
      - .offset:         320
        .size:           2
        .value_kind:     hidden_group_size_z
      - .offset:         322
        .size:           2
        .value_kind:     hidden_remainder_x
      - .offset:         324
        .size:           2
        .value_kind:     hidden_remainder_y
      - .offset:         326
        .size:           2
        .value_kind:     hidden_remainder_z
      - .offset:         344
        .size:           8
        .value_kind:     hidden_global_offset_x
      - .offset:         352
        .size:           8
        .value_kind:     hidden_global_offset_y
      - .offset:         360
        .size:           8
        .value_kind:     hidden_global_offset_z
      - .offset:         368
        .size:           2
        .value_kind:     hidden_grid_dims
      - .offset:         392
        .size:           8
        .value_kind:     hidden_multigrid_sync_arg
      - .offset:         424
        .size:           4
        .value_kind:     hidden_dynamic_lds_size
    .group_segment_fixed_size: 0
    .kernarg_segment_align: 8
    .kernarg_segment_size: 560
    .language:       OpenCL C
    .language_version:
      - 2
      - 0
    .max_flat_workgroup_size: 512
    .name:           _Z10hybrid_fwd6Params
    .private_segment_fixed_size: 0
    .sgpr_count:     108
    .sgpr_spill_count: 17
    .symbol:         _Z10hybrid_fwd6Params.kd
    .uniform_work_group_size: 1
    .uses_dynamic_stack: false
    .vgpr_count:     256
    .vgpr_spill_count: 0
    .wavefront_size: 64
